# SWA attention also moved to v_mfma_f32_16x16x32_bf16 with the same scheme (window+causal masks per half, sink as initial reference max, lazy rescale)
# speedup vs baseline: 1.1361x; 1.0060x over previous
.LBB0_379:
.LBB0_380:
	v_add_u32_e32 v172, v103, v124
	ds_read_b128 v[140:143], v172
	ds_read_b128 v[144:147], v172 offset:2304
	ds_read_b128 v[148:151], v172 offset:4608
	ds_read_b128 v[152:155], v172 offset:6912
	s_waitcnt lgkmcnt(3)
	v_mfma_f32_16x16x32_bf16 v[2:5], v[140:143], v[74:77], v[2:5]
	v_mfma_f32_16x16x32_bf16 v[6:9], v[140:143], v[78:81], v[6:9]
	s_waitcnt lgkmcnt(2)
	v_mfma_f32_16x16x32_bf16 v[10:13], v[144:147], v[74:77], v[10:13]
	v_mfma_f32_16x16x32_bf16 v[14:17], v[144:147], v[78:81], v[14:17]
	s_waitcnt lgkmcnt(1)
	v_mfma_f32_16x16x32_bf16 v[18:21], v[148:151], v[74:77], v[18:21]
	v_mfma_f32_16x16x32_bf16 v[22:25], v[148:151], v[78:81], v[22:25]
	s_waitcnt lgkmcnt(0)
	v_mfma_f32_16x16x32_bf16 v[26:29], v[152:155], v[74:77], v[26:29]
	v_mfma_f32_16x16x32_bf16 v[30:33], v[152:155], v[78:81], v[30:33]
	ds_bpermute_b32 v166, v126, v87
	ds_bpermute_b32 v167, v126, v136
	s_waitcnt lgkmcnt(0)
	v_add_f32_e32 v87, v87, v166
	v_add_f32_e32 v136, v136, v167
	ds_bpermute_b32 v166, v85, v87
	ds_bpermute_b32 v167, v85, v136
	s_waitcnt lgkmcnt(0)
	v_add_f32_e32 v87, v87, v166
	v_add_f32_e32 v136, v136, v167
	s_barrier
	v_div_scale_f32 v34, s[8:9], v87, v87, 1.0
	v_rcp_f32_e32 v35, v34
	s_nop 0
	v_fma_f32 v36, -v34, v35, 1.0
	v_fmac_f32_e32 v35, v36, v35
	v_div_scale_f32 v36, vcc, 1.0, v87, 1.0
	v_mul_f32_e32 v37, v36, v35
	v_fma_f32 v38, -v34, v37, v36
	v_fmac_f32_e32 v37, v38, v35
	v_fma_f32 v34, -v34, v37, v36
	v_div_fmas_f32 v34, v34, v35, v37
	v_div_fixup_f32 v34, v34, v87, 1.0
	v_div_scale_f32 v42, s[8:9], v136, v136, 1.0
	v_rcp_f32_e32 v43, v42
	s_nop 0
	v_fma_f32 v44, -v42, v43, 1.0
	v_fmac_f32_e32 v43, v44, v43
	v_div_scale_f32 v44, vcc, 1.0, v136, 1.0
	v_mul_f32_e32 v45, v44, v43
	v_fma_f32 v46, -v42, v45, v44
	v_fmac_f32_e32 v45, v46, v43
	v_fma_f32 v42, -v42, v45, v44
	v_div_fmas_f32 v42, v42, v43, v45
	v_div_fixup_f32 v42, v42, v136, 1.0
	s_lshl_b32 s4, s88, 7
	s_add_u32 s4, s76, s4
	s_addc_u32 s5, s77, 0
	v_and_b32_e32 v138, 15, v162
	v_add_u32_e32 v138, v93, v138
	v_ashrrev_i32_e32 v139, 31, v138
	v_lshlrev_b64 v[138:139], 11, v[138:139]
	v_lshl_add_u64 v[138:139], s[4:5], 0, v[138:139]
	v_bfe_u32 v166, v162, 4, 2
	v_lshlrev_b32_e32 v166, 3, v166
	v_mov_b32_e32 v167, 0
	v_lshl_add_u64 v[138:139], v[138:139], 0, v[166:167]
	v_add_co_u32_e32 v166, vcc, 0x8000, v138
	s_nop 1
	v_addc_co_u32_e32 v167, vcc, 0, v139, vcc
	v_mul_f32_e32 v2, v2, v34
	v_mul_f32_e32 v3, v3, v34
	v_mul_f32_e32 v4, v4, v34
	v_mul_f32_e32 v5, v5, v34
	v_cvt_pk_bf16_f32 v168, v2, v3
	v_cvt_pk_bf16_f32 v169, v4, v5
	global_store_dwordx2 v[138:139], v[168:169], off
	v_mul_f32_e32 v6, v6, v42
	v_mul_f32_e32 v7, v7, v42
	v_mul_f32_e32 v8, v8, v42
	v_mul_f32_e32 v9, v9, v42
	v_cvt_pk_bf16_f32 v170, v6, v7
	v_cvt_pk_bf16_f32 v171, v8, v9
	global_store_dwordx2 v[166:167], v[170:171], off
	v_mul_f32_e32 v10, v10, v34
	v_mul_f32_e32 v11, v11, v34
	v_mul_f32_e32 v12, v12, v34
	v_mul_f32_e32 v13, v13, v34
	v_cvt_pk_bf16_f32 v168, v10, v11
	v_cvt_pk_bf16_f32 v169, v12, v13
	global_store_dwordx2 v[138:139], v[168:169], off offset:32
	v_mul_f32_e32 v14, v14, v42
	v_mul_f32_e32 v15, v15, v42
	v_mul_f32_e32 v16, v16, v42
	v_mul_f32_e32 v17, v17, v42
	v_cvt_pk_bf16_f32 v170, v14, v15
	v_cvt_pk_bf16_f32 v171, v16, v17
	global_store_dwordx2 v[166:167], v[170:171], off offset:32
	v_mul_f32_e32 v18, v18, v34
	v_mul_f32_e32 v19, v19, v34
	v_mul_f32_e32 v20, v20, v34
	v_mul_f32_e32 v21, v21, v34
	v_cvt_pk_bf16_f32 v168, v18, v19
	v_cvt_pk_bf16_f32 v169, v20, v21
	global_store_dwordx2 v[138:139], v[168:169], off offset:64
	v_mul_f32_e32 v22, v22, v42
	v_mul_f32_e32 v23, v23, v42
	v_mul_f32_e32 v24, v24, v42
	v_mul_f32_e32 v25, v25, v42
	v_cvt_pk_bf16_f32 v170, v22, v23
	v_cvt_pk_bf16_f32 v171, v24, v25
	global_store_dwordx2 v[166:167], v[170:171], off offset:64
	v_mul_f32_e32 v26, v26, v34
	v_mul_f32_e32 v27, v27, v34
	v_mul_f32_e32 v28, v28, v34
	v_mul_f32_e32 v29, v29, v34
	v_cvt_pk_bf16_f32 v168, v26, v27
	v_cvt_pk_bf16_f32 v169, v28, v29
	global_store_dwordx2 v[138:139], v[168:169], off offset:96
	v_mul_f32_e32 v30, v30, v42
	v_mul_f32_e32 v31, v31, v42
	v_mul_f32_e32 v32, v32, v42
	v_mul_f32_e32 v33, v33, v42
	v_cvt_pk_bf16_f32 v170, v30, v31
	v_cvt_pk_bf16_f32 v171, v32, v33
	global_store_dwordx2 v[166:167], v[170:171], off offset:96
	s_add_i32 s87, s87, s30
	s_cmpk_gt_i32 s87, 0x3ff
	s_cbranch_scc1 .LBB0_401
.LBB0_381:
	s_ashr_i32 s4, s87, 4
	s_lshl_b32 s9, s4, 8
	s_and_b32 s88, s87, 15
	s_add_i32 s5, s9, 0xffffff80
	s_cmp_gt_i32 s4, 0
	s_cselect_b32 s8, s5, 0
	s_lshl_b32 s4, s88, 7
	s_add_u32 s58, s60, s4
	s_addc_u32 s59, s61, 0
	s_lshl_b32 s4, s87, 19
	s_and_b32 s10, s4, 0x600000
	s_add_u32 s4, s72, s10
	s_addc_u32 s5, s73, 0
	s_add_u32 s10, s74, s10
	v_readlane_b32 s12, v246, 0
	s_addc_u32 s11, s75, 0
	s_or_b32 s54, s88, s86
	v_readlane_b32 s16, v246, 4
	v_readlane_b32 s17, v246, 5
	v_readlane_b32 s20, v246, 8
	v_readlane_b32 s21, v246, 9
	s_lshl_b64 s[80:81], s[54:55], 2
	s_mov_b64 s[16:17], s[20:21]
	s_add_u32 s80, s16, s80
	s_addc_u32 s81, s17, s81
	v_mov_b32_e32 v6, v162
	global_load_dword v14, v1, s[80:81]
	s_sub_i32 s80, s9, s8
	v_ashrrev_i32_e32 v0, 1, v6
	v_and_b32_e32 v0, 0xffffffe0, v0
	v_and_b32_e32 v13, 31, v6
	v_add_u32_e32 v93, s9, v0
	v_or_b32_e32 v86, v93, v13
	v_ashrrev_i32_e32 v87, 31, v86
	v_lshlrev_b64 v[82:83], 11, v[86:87]
	s_mov_b32 s9, s55
	v_bfe_u32 v12, v6, 5, 1
	v_lshl_add_u64 v[2:3], s[58:59], 0, v[82:83]
	v_and_b32_e32 v120, 15, v6
	v_bfe_u32 v121, v6, 4, 2
	v_add_u32_e32 v122, v93, v120
	v_ashrrev_i32_e32 v123, 31, v122
	v_lshlrev_b64 v[116:117], 11, v[122:123]
	v_lshl_add_u64 v[116:117], s[58:59], 0, v[116:117]
	v_lshlrev_b32_e32 v120, 4, v121
	v_mov_b32_e32 v121, 0
	v_lshl_add_u64 v[116:117], v[116:117], 0, v[120:121]
	v_add_co_u32_e32 v118, vcc, 0x8000, v116
	s_nop 1
	v_addc_co_u32_e32 v119, vcc, 0, v117, vcc
	s_addk_i32 s80, 0x100
	s_lshl_b64 s[58:59], s[8:9], 7
	v_lshlrev_b32_e32 v0, 4, v12
	s_add_u32 s58, s4, s58
	v_ashrrev_i32_e32 v7, 31, v6
	v_lshl_add_u64 v[16:17], v[2:3], 0, v[0:1]
	s_addc_u32 s59, s5, s59
	v_lshlrev_b64 v[2:3], 4, v[6:7]
	v_lshl_add_u64 v[4:5], s[58:59], 0, v[2:3]
	global_load_dwordx4 v[50:53], v[116:117], off
	global_load_dwordx4 v[54:57], v[116:117], off offset:64
	global_load_dwordx4 v[58:61], v[118:119], off
	global_load_dwordx4 v[62:65], v[4:5], off
	v_lshrrev_b32_e32 v4, 29, v7
	v_add_u32_e32 v7, v6, v4
	s_lshl_b64 s[58:59], s[8:9], 1
	v_ashrrev_i32_e32 v18, 3, v7
	v_and_b32_e32 v7, -8, v7
	s_add_u32 s58, s10, s58
	v_ashrrev_i32_e32 v19, 31, v18
	v_sub_u32_e32 v7, v6, v7
	s_addc_u32 s59, s11, s59
	v_lshlrev_b64 v[4:5], 15, v[18:19]
	v_lshlrev_b32_e32 v8, 3, v7
	v_lshl_add_u64 v[10:11], s[58:59], 0, v[4:5]
	v_ashrrev_i32_e32 v9, 31, v8
	v_lshl_add_u64 v[10:11], v[8:9], 1, v[10:11]
	global_load_dwordx4 v[66:69], v[118:119], off offset:64
	global_load_dwordx4 v[70:73], v[10:11], off
	v_readlane_b32 s13, v246, 1
	v_readlane_b32 s14, v246, 2
	v_readlane_b32 s15, v246, 3
	v_readlane_b32 s18, v246, 6
	v_readlane_b32 s19, v246, 7
	v_readlane_b32 s22, v246, 10
	v_readlane_b32 s23, v246, 11
	v_readlane_b32 s24, v246, 12
	v_readlane_b32 s25, v246, 13
	v_readlane_b32 s26, v246, 14
	v_readlane_b32 s27, v246, 15
	v_mul_lo_u32 v15, v18, s49
	v_lshlrev_b32_e32 v7, 4, v7
	v_add3_u32 v94, s78, v15, v7
	s_cmpk_lt_i32 s80, 0x80
	s_waitcnt vmcnt(2)
	ds_write_b128 v94, v[62:65]
	s_waitcnt vmcnt(0)
	ds_write_b128 v94, v[70:73] offset:18432
	s_cbranch_scc1 .LBB0_383
	s_or_b32 s54, s8, 64
	s_lshl_b64 s[58:59], s[54:55], 7
	s_add_u32 s58, s4, s58
	s_addc_u32 s59, s5, s59
	v_lshl_add_u64 v[16:17], s[58:59], 0, v[2:3]
	global_load_dwordx4 v[62:65], v[16:17], off
	global_load_dwordx4 v[70:73], v[10:11], off offset:128

.LBB0_385:
	v_cndmask_b32_e64 v87, 0, 1.0, vcc
	s_andn2_b64 vcc, exec, s[58:59]
	s_mov_b32 s58, 0
	s_cbranch_vccnz .LBB0_400
	v_lshl_add_u64 v[88:89], s[4:5], 0, v[2:3]
	v_lshl_add_u64 v[2:3], s[10:11], 0, v[4:5]
	s_ashr_i32 s9, s80, 6
	v_lshl_add_u64 v[90:91], v[8:9], 1, v[2:3]
	v_mul_u32_u24_e32 v92, 0x90, v13
	v_lshlrev_b32_e32 v2, 2, v6
	v_readlane_b32 s4, v246, 58
	s_add_i32 s89, s9, -2
	v_mul_f32_e32 v100, 0x3fb8aa3b, v14
	v_add_u32_e32 v95, 63, v93
	v_add3_u32 v96, s78, v92, v0
	v_or_b32_e32 v97, 31, v93
	v_lshlrev_b32_e32 v84, 2, v12
	v_xor_b32_e32 v85, 0x80, v2
	v_mov_b32_e32 v2, v1
	v_mov_b32_e32 v3, v1
	v_mov_b32_e32 v4, v1
	v_mov_b32_e32 v5, v1
	v_mov_b32_e32 v6, v1
	v_mov_b32_e32 v7, v1
	v_mov_b32_e32 v8, v1
	v_mov_b32_e32 v9, v1
	v_mov_b32_e32 v10, v1
	v_mov_b32_e32 v11, v1
	v_mov_b32_e32 v12, v1
	v_mov_b32_e32 v13, v1
	v_mov_b32_e32 v14, v1
	v_mov_b32_e32 v15, v1
	v_mov_b32_e32 v16, v1
	v_mov_b32_e32 v17, v1
	v_mov_b32_e32 v18, v1
	v_mov_b32_e32 v19, v1
	v_mov_b32_e32 v20, v1
	v_mov_b32_e32 v21, v1
	v_mov_b32_e32 v22, v1
	v_mov_b32_e32 v23, v1
	v_mov_b32_e32 v24, v1
	v_mov_b32_e32 v25, v1
	v_mov_b32_e32 v26, v1
	v_mov_b32_e32 v27, v1
	v_mov_b32_e32 v28, v1
	v_mov_b32_e32 v29, v1
	v_mov_b32_e32 v30, v1
	v_mov_b32_e32 v31, v1
	v_mov_b32_e32 v32, v1
	v_mov_b32_e32 v33, v1
	v_mov_b32_e32 v103, s4
	v_mov_b32_e32 v78, 0
	v_mov_b32_e32 v79, 0
	v_mov_b32_e32 v80, 0
	v_mov_b32_e32 v81, 0
	v_mov_b32_e32 v74, 0
	v_mov_b32_e32 v75, 0
	v_mov_b32_e32 v76, 0
	v_mov_b32_e32 v77, 0
	v_and_b32_e32 v138, 15, v162
	v_bfe_u32 v139, v162, 4, 2
	v_lshrrev_b32_e32 v166, 3, v138
	v_lshl_add_u32 v166, v166, 3, v138
	v_mul_u32_u24_e32 v166, 0x90, v166
	v_lshlrev_b32_e32 v167, 4, v139
	v_add3_u32 v96, s78, v166, v167
	v_mul_u32_u24_e32 v166, 0x90, v138
	v_add_u32_e32 v124, v166, v167
	v_lshrrev_b32_e32 v166, 1, v139
	v_lshlrev_b32_e32 v166, 3, v166
	v_lshl_add_u32 v166, v139, 2, v166
	v_sub_u32_e32 v125, v166, v138
	v_and_b32_e32 v166, 63, v162
	v_xor_b32_e32 v167, 16, v166
	v_lshlrev_b32_e32 v126, 2, v167
	v_cmp_gt_u32_e32 vcc, 16, v166
	v_mov_b32_e32 v127, v100
	s_nop 1
	v_cndmask_b32_e64 v87, 0, 1.0, vcc
	v_cndmask_b32_e64 v136, 0, 1.0, vcc
	v_readfirstlane_b32 s98, v93
	v_sub_f32_e32 v128, 0, v100
	v_sub_f32_e32 v129, 0, v100
	v_sub_f32_e32 v130, 0, v100
	v_sub_f32_e32 v131, 0, v100
	v_sub_f32_e32 v132, 0, v100
	v_sub_f32_e32 v133, 0, v100
	v_sub_f32_e32 v134, 0, v100
	v_sub_f32_e32 v135, 0, v100
	s_and_b32 s4, s58, 1
	s_add_i32 s90, s58, 1
	s_cmp_ge_i32 s90, s9
	s_cbranch_scc1 .LBB0_388

.Lw3_h0:
	s_mov_b32 s101, s10
	s_sub_i32 s99, s98, s101
	s_add_i32 s100, s99, 63
	s_cmp_lt_u32 s100, 222
	s_cbranch_scc0 .Lw3_h0_end
	v_mov_b32_e32 v173, v98
	v_add_u32_e32 v172, v103, v124
	s_add_i32 s4, s11, 0x4800
	ds_read_b128 v[140:143], v173
	ds_read_b128 v[144:147], v173 offset:1152
	ds_read_b128 v[148:151], v173 offset:64
	ds_read_b128 v[152:155], v173 offset:1216
	v_mov_b32_e32 v103, s4
	s_waitcnt lgkmcnt(3)
	v_mfma_f32_16x16x32_bf16 v[34:37], v[140:143], v[50:53], v[128:131]
	v_mfma_f32_16x16x32_bf16 v[38:41], v[140:143], v[58:61], v[132:135]
	ds_read_b128 v[156:159], v172
	s_waitcnt lgkmcnt(3)
	v_mfma_f32_16x16x32_bf16 v[42:45], v[144:147], v[50:53], v[128:131]
	v_mfma_f32_16x16x32_bf16 v[46:49], v[144:147], v[58:61], v[132:135]
	ds_read_b128 v[140:143], v172 offset:2304
	s_waitcnt lgkmcnt(3)
	v_mfma_f32_16x16x32_bf16 v[34:37], v[148:151], v[54:57], v[34:37]
	v_mfma_f32_16x16x32_bf16 v[38:41], v[148:151], v[66:69], v[38:41]
	ds_read_b128 v[144:147], v172 offset:4608
	s_waitcnt lgkmcnt(3)
	v_mfma_f32_16x16x32_bf16 v[42:45], v[152:155], v[54:57], v[42:45]
	v_mfma_f32_16x16x32_bf16 v[46:49], v[152:155], v[66:69], v[46:49]
	ds_read_b128 v[148:151], v172 offset:6912
	s_waitcnt lgkmcnt(3)
	v_mfma_f32_16x16x32_bf16 v[2:5], v[156:159], v[74:77], v[2:5]
	v_mfma_f32_16x16x32_bf16 v[6:9], v[156:159], v[78:81], v[6:9]
	s_waitcnt lgkmcnt(2)
	v_mfma_f32_16x16x32_bf16 v[10:13], v[140:143], v[74:77], v[10:13]
	v_mfma_f32_16x16x32_bf16 v[14:17], v[140:143], v[78:81], v[14:17]
	s_waitcnt lgkmcnt(1)
	v_mfma_f32_16x16x32_bf16 v[18:21], v[144:147], v[74:77], v[18:21]
	v_mfma_f32_16x16x32_bf16 v[22:25], v[144:147], v[78:81], v[22:25]
	s_waitcnt lgkmcnt(0)
	v_mfma_f32_16x16x32_bf16 v[26:29], v[148:151], v[74:77], v[26:29]
	v_mfma_f32_16x16x32_bf16 v[30:33], v[148:151], v[78:81], v[30:33]
	s_cmp_lt_i32 s99, 31
	s_cbranch_scc1 .Lw3_h0_mask
	s_cmp_ge_i32 s99, 97
	s_cbranch_scc1 .Lw3_h0_wmask
.Lw3_h0_sm:
	v_max3_f32 v137, v34, v35, v36
	v_max3_f32 v138, v42, v43, v44
	v_max3_f32 v137, v137, v37, v38
	v_max3_f32 v138, v138, v45, v46
	v_max3_f32 v137, v137, v39, v40
	v_max3_f32 v138, v138, v47, v48
	v_max3_f32 v137, v137, v41, v49
	v_max_f32_e32 v137, v137, v138
	v_cmp_lt_f32_e32 vcc, 0x41000000, v137
	s_cbranch_vccnz .Lw3_h0_grow
.Lw3_h0_exp:
	v_exp_f32_e32 v34, v34
	v_exp_f32_e32 v35, v35
	v_exp_f32_e32 v36, v36
	v_exp_f32_e32 v37, v37
	v_exp_f32_e32 v38, v38
	v_exp_f32_e32 v39, v39
	v_exp_f32_e32 v40, v40
	v_exp_f32_e32 v41, v41
	v_exp_f32_e32 v42, v42
	v_exp_f32_e32 v43, v43
	v_exp_f32_e32 v44, v44
	v_exp_f32_e32 v45, v45
	v_exp_f32_e32 v46, v46
	v_exp_f32_e32 v47, v47
	v_exp_f32_e32 v48, v48
	v_exp_f32_e32 v49, v49
	v_add_f32_e32 v87, v87, v34
	v_add_f32_e32 v136, v136, v38
	v_add_f32_e32 v87, v87, v42
	v_add_f32_e32 v136, v136, v46
	v_add_f32_e32 v87, v87, v35
	v_add_f32_e32 v136, v136, v39
	v_add_f32_e32 v87, v87, v43
	v_add_f32_e32 v136, v136, v47
	v_add_f32_e32 v87, v87, v36
	v_add_f32_e32 v136, v136, v40
	v_add_f32_e32 v87, v87, v44
	v_add_f32_e32 v136, v136, v48
	v_add_f32_e32 v87, v87, v37
	v_add_f32_e32 v136, v136, v41
	v_add_f32_e32 v87, v87, v45
	v_add_f32_e32 v136, v136, v49
	v_cvt_pk_bf16_f32 v74, v34, v35
	v_cvt_pk_bf16_f32 v75, v36, v37
	v_cvt_pk_bf16_f32 v76, v42, v43
	v_cvt_pk_bf16_f32 v77, v44, v45
	v_cvt_pk_bf16_f32 v78, v38, v39
	v_cvt_pk_bf16_f32 v79, v40, v41
	v_cvt_pk_bf16_f32 v80, v46, v47
	v_cvt_pk_bf16_f32 v81, v48, v49
.Lw3_h0_end:
.Lw3_h1:
	s_add_i32 s101, s10, 32
	s_sub_i32 s99, s98, s101
	s_add_i32 s100, s99, 63
	s_cmp_lt_u32 s100, 222
	s_cbranch_scc0 .Lw3_h1_end
	v_add_u32_e32 v173, 0x1200, v98
	v_add_u32_e32 v172, v103, v124
	s_add_i32 s4, s11, 0x4840
	ds_read_b128 v[140:143], v173
	ds_read_b128 v[144:147], v173 offset:1152
	ds_read_b128 v[148:151], v173 offset:64
	ds_read_b128 v[152:155], v173 offset:1216
	v_mov_b32_e32 v103, s4
	s_waitcnt lgkmcnt(3)
	v_mfma_f32_16x16x32_bf16 v[34:37], v[140:143], v[50:53], v[128:131]
	v_mfma_f32_16x16x32_bf16 v[38:41], v[140:143], v[58:61], v[132:135]
	ds_read_b128 v[156:159], v172
	s_waitcnt lgkmcnt(3)
	v_mfma_f32_16x16x32_bf16 v[42:45], v[144:147], v[50:53], v[128:131]
	v_mfma_f32_16x16x32_bf16 v[46:49], v[144:147], v[58:61], v[132:135]
	ds_read_b128 v[140:143], v172 offset:2304
	s_waitcnt lgkmcnt(3)
	v_mfma_f32_16x16x32_bf16 v[34:37], v[148:151], v[54:57], v[34:37]
	v_mfma_f32_16x16x32_bf16 v[38:41], v[148:151], v[66:69], v[38:41]
	ds_read_b128 v[144:147], v172 offset:4608
	s_waitcnt lgkmcnt(3)
	v_mfma_f32_16x16x32_bf16 v[42:45], v[152:155], v[54:57], v[42:45]
	v_mfma_f32_16x16x32_bf16 v[46:49], v[152:155], v[66:69], v[46:49]
	ds_read_b128 v[148:151], v172 offset:6912
	s_waitcnt lgkmcnt(3)
	v_mfma_f32_16x16x32_bf16 v[2:5], v[156:159], v[74:77], v[2:5]
	v_mfma_f32_16x16x32_bf16 v[6:9], v[156:159], v[78:81], v[6:9]
	s_waitcnt lgkmcnt(2)
	v_mfma_f32_16x16x32_bf16 v[10:13], v[140:143], v[74:77], v[10:13]
	v_mfma_f32_16x16x32_bf16 v[14:17], v[140:143], v[78:81], v[14:17]
	s_waitcnt lgkmcnt(1)
	v_mfma_f32_16x16x32_bf16 v[18:21], v[144:147], v[74:77], v[18:21]
	v_mfma_f32_16x16x32_bf16 v[22:25], v[144:147], v[78:81], v[22:25]
	s_waitcnt lgkmcnt(0)
	v_mfma_f32_16x16x32_bf16 v[26:29], v[148:151], v[74:77], v[26:29]
	v_mfma_f32_16x16x32_bf16 v[30:33], v[148:151], v[78:81], v[30:33]
	s_cmp_lt_i32 s99, 31
	s_cbranch_scc1 .Lw3_h1_mask
	s_cmp_ge_i32 s99, 97
	s_cbranch_scc1 .Lw3_h1_wmask

.Lw3_h0_mask:
	s_sub_i32 s100, s99, 0
	v_cmp_ge_i32_e32 vcc, s100, v125
	s_nop 1
	v_cndmask_b32_e32 v34, v184, v34, vcc
	s_sub_i32 s100, s99, 1
	v_cmp_ge_i32_e32 vcc, s100, v125
	s_nop 1
	v_cndmask_b32_e32 v35, v184, v35, vcc
	s_sub_i32 s100, s99, 2
	v_cmp_ge_i32_e32 vcc, s100, v125
	s_nop 1
	v_cndmask_b32_e32 v36, v184, v36, vcc
	s_sub_i32 s100, s99, 3
	v_cmp_ge_i32_e32 vcc, s100, v125
	s_nop 1
	v_cndmask_b32_e32 v37, v184, v37, vcc
	s_add_i32 s100, s99, 16
	v_cmp_ge_i32_e32 vcc, s100, v125
	s_nop 1
	v_cndmask_b32_e32 v38, v184, v38, vcc
	s_add_i32 s100, s99, 15
	v_cmp_ge_i32_e32 vcc, s100, v125
	s_nop 1
	v_cndmask_b32_e32 v39, v184, v39, vcc
	s_add_i32 s100, s99, 14
	v_cmp_ge_i32_e32 vcc, s100, v125
	s_nop 1
	v_cndmask_b32_e32 v40, v184, v40, vcc
	s_add_i32 s100, s99, 13
	v_cmp_ge_i32_e32 vcc, s100, v125
	s_nop 1
	v_cndmask_b32_e32 v41, v184, v41, vcc
	s_sub_i32 s100, s99, 8
	v_cmp_ge_i32_e32 vcc, s100, v125
	s_nop 1
	v_cndmask_b32_e32 v42, v184, v42, vcc
	s_sub_i32 s100, s99, 9
	v_cmp_ge_i32_e32 vcc, s100, v125
	s_nop 1
	v_cndmask_b32_e32 v43, v184, v43, vcc
	s_sub_i32 s100, s99, 10
	v_cmp_ge_i32_e32 vcc, s100, v125
	s_nop 1
	v_cndmask_b32_e32 v44, v184, v44, vcc
	s_sub_i32 s100, s99, 11
	v_cmp_ge_i32_e32 vcc, s100, v125
	s_nop 1
	v_cndmask_b32_e32 v45, v184, v45, vcc
	s_add_i32 s100, s99, 8
	v_cmp_ge_i32_e32 vcc, s100, v125
	s_nop 1
	v_cndmask_b32_e32 v46, v184, v46, vcc
	s_add_i32 s100, s99, 7
	v_cmp_ge_i32_e32 vcc, s100, v125
	s_nop 1
	v_cndmask_b32_e32 v47, v184, v47, vcc
	s_add_i32 s100, s99, 6
	v_cmp_ge_i32_e32 vcc, s100, v125
	s_nop 1
	v_cndmask_b32_e32 v48, v184, v48, vcc
	s_add_i32 s100, s99, 5
	v_cmp_ge_i32_e32 vcc, s100, v125
	s_nop 1
	v_cndmask_b32_e32 v49, v184, v49, vcc
	s_branch .Lw3_h0_sm
.Lw3_h0_wmask:
	s_sub_i32 s100, s99, 127
	v_cmp_le_i32_e32 vcc, s100, v125
	s_nop 1
	v_cndmask_b32_e32 v34, v184, v34, vcc
	s_sub_i32 s100, s99, 128
	v_cmp_le_i32_e32 vcc, s100, v125
	s_nop 1
	v_cndmask_b32_e32 v35, v184, v35, vcc
	s_sub_i32 s100, s99, 129
	v_cmp_le_i32_e32 vcc, s100, v125
	s_nop 1
	v_cndmask_b32_e32 v36, v184, v36, vcc
	s_sub_i32 s100, s99, 130
	v_cmp_le_i32_e32 vcc, s100, v125
	s_nop 1
	v_cndmask_b32_e32 v37, v184, v37, vcc
	s_sub_i32 s100, s99, 111
	v_cmp_le_i32_e32 vcc, s100, v125
	s_nop 1
	v_cndmask_b32_e32 v38, v184, v38, vcc
	s_sub_i32 s100, s99, 112
	v_cmp_le_i32_e32 vcc, s100, v125
	s_nop 1
	v_cndmask_b32_e32 v39, v184, v39, vcc
	s_sub_i32 s100, s99, 113
	v_cmp_le_i32_e32 vcc, s100, v125
	s_nop 1
	v_cndmask_b32_e32 v40, v184, v40, vcc
	s_sub_i32 s100, s99, 114
	v_cmp_le_i32_e32 vcc, s100, v125
	s_nop 1
	v_cndmask_b32_e32 v41, v184, v41, vcc
	s_sub_i32 s100, s99, 135
	v_cmp_le_i32_e32 vcc, s100, v125
	s_nop 1
	v_cndmask_b32_e32 v42, v184, v42, vcc
	s_sub_i32 s100, s99, 136
	v_cmp_le_i32_e32 vcc, s100, v125
	s_nop 1
	v_cndmask_b32_e32 v43, v184, v43, vcc
	s_sub_i32 s100, s99, 137
	v_cmp_le_i32_e32 vcc, s100, v125
	s_nop 1
	v_cndmask_b32_e32 v44, v184, v44, vcc
	s_sub_i32 s100, s99, 138
	v_cmp_le_i32_e32 vcc, s100, v125
	s_nop 1
	v_cndmask_b32_e32 v45, v184, v45, vcc
	s_sub_i32 s100, s99, 119
	v_cmp_le_i32_e32 vcc, s100, v125
	s_nop 1
	v_cndmask_b32_e32 v46, v184, v46, vcc
	s_sub_i32 s100, s99, 120
	v_cmp_le_i32_e32 vcc, s100, v125
	s_nop 1
	v_cndmask_b32_e32 v47, v184, v47, vcc
	s_sub_i32 s100, s99, 121
	v_cmp_le_i32_e32 vcc, s100, v125
	s_nop 1
	v_cndmask_b32_e32 v48, v184, v48, vcc
	s_sub_i32 s100, s99, 122
	v_cmp_le_i32_e32 vcc, s100, v125
	s_nop 1
	v_cndmask_b32_e32 v49, v184, v49, vcc
	s_branch .Lw3_h0_sm
.Lw3_h0_grow:
	v_max3_f32 v138, v34, v35, v36
	v_max3_f32 v138, v138, v37, v42
	v_max3_f32 v138, v138, v43, v44
	v_max_f32_e32 v138, v138, v45
	v_max3_f32 v139, v38, v39, v40
	v_max3_f32 v139, v139, v41, v46
	v_max3_f32 v139, v139, v47, v48
	v_max_f32_e32 v139, v139, v49
	ds_bpermute_b32 v166, v126, v138
	ds_bpermute_b32 v167, v126, v139
	s_waitcnt lgkmcnt(0)
	v_max_f32_e32 v138, v138, v166
	v_max_f32_e32 v139, v139, v167
	ds_bpermute_b32 v166, v85, v138
	ds_bpermute_b32 v167, v85, v139
	s_waitcnt lgkmcnt(0)
	v_max_f32_e32 v138, v138, v166
	v_max_f32_e32 v139, v139, v167
	v_max_f32_e32 v138, 0, v138
	v_max_f32_e32 v139, 0, v139
	v_sub_f32_e32 v168, 0, v138
	v_sub_f32_e32 v170, 0, v139
	v_exp_f32_e32 v168, v168
	v_exp_f32_e32 v170, v170
	s_nop 0
	v_mul_f32_e32 v87, v87, v168
	v_mul_f32_e32 v136, v136, v170
	v_pk_mul_f32 v[2:3], v[2:3], v[168:169] op_sel_hi:[1,0]
	v_pk_mul_f32 v[4:5], v[4:5], v[168:169] op_sel_hi:[1,0]
	v_pk_mul_f32 v[6:7], v[6:7], v[170:171] op_sel_hi:[1,0]
	v_pk_mul_f32 v[8:9], v[8:9], v[170:171] op_sel_hi:[1,0]
	v_pk_mul_f32 v[10:11], v[10:11], v[168:169] op_sel_hi:[1,0]
	v_pk_mul_f32 v[12:13], v[12:13], v[168:169] op_sel_hi:[1,0]
	v_pk_mul_f32 v[14:15], v[14:15], v[170:171] op_sel_hi:[1,0]
	v_pk_mul_f32 v[16:17], v[16:17], v[170:171] op_sel_hi:[1,0]
	v_pk_mul_f32 v[18:19], v[18:19], v[168:169] op_sel_hi:[1,0]
	v_pk_mul_f32 v[20:21], v[20:21], v[168:169] op_sel_hi:[1,0]
	v_pk_mul_f32 v[22:23], v[22:23], v[170:171] op_sel_hi:[1,0]
	v_pk_mul_f32 v[24:25], v[24:25], v[170:171] op_sel_hi:[1,0]
	v_pk_mul_f32 v[26:27], v[26:27], v[168:169] op_sel_hi:[1,0]
	v_pk_mul_f32 v[28:29], v[28:29], v[168:169] op_sel_hi:[1,0]
	v_pk_mul_f32 v[30:31], v[30:31], v[170:171] op_sel_hi:[1,0]
	v_pk_mul_f32 v[32:33], v[32:33], v[170:171] op_sel_hi:[1,0]
	v_add_f32_e32 v100, v100, v138
	v_add_f32_e32 v127, v127, v139
	v_sub_f32_e32 v128, 0, v100
	v_sub_f32_e32 v132, 0, v127
	v_sub_f32_e32 v129, 0, v100
	v_sub_f32_e32 v133, 0, v127
	v_sub_f32_e32 v130, 0, v100
	v_sub_f32_e32 v134, 0, v127
	v_sub_f32_e32 v131, 0, v100
	v_sub_f32_e32 v135, 0, v127
	v_sub_f32_e32 v34, v34, v138
	v_sub_f32_e32 v38, v38, v139
	v_sub_f32_e32 v35, v35, v138
	v_sub_f32_e32 v39, v39, v139
	v_sub_f32_e32 v36, v36, v138
	v_sub_f32_e32 v40, v40, v139
	v_sub_f32_e32 v37, v37, v138
	v_sub_f32_e32 v41, v41, v139
	v_sub_f32_e32 v42, v42, v138
	v_sub_f32_e32 v46, v46, v139
	v_sub_f32_e32 v43, v43, v138
	v_sub_f32_e32 v47, v47, v139
	v_sub_f32_e32 v44, v44, v138
	v_sub_f32_e32 v48, v48, v139
	v_sub_f32_e32 v45, v45, v138
	v_sub_f32_e32 v49, v49, v139
	s_branch .Lw3_h0_exp
